# pool pass row loop: four rows of loads in flight (unrolled x4 over four register sets, clamped row index, counted vmcnt 13) instead of one
# baseline (speedup 1.0000x reference)
; __device__ __forceinline__ void unpack8(const u32x4& w, float (&v)[8]) { v[0] = bf_lo(w.x); v[1] = bf_hi(w.x); v[2] = bf_lo(w.y); v[3] = bf_hi(w.y); v[4] = bf_lo(w.z); v[5] = bf_hi(w.z); v[6] = bf_lo(w.w); v[7] = bf_hi(w.w); }
; __device__ __forceinline__ void phase_pool(const Args& a, int l, int vcu, int NGW, int wv) {
;     ...
;         float S[8];
; #pragma unroll
;         for (int i = 0; i < 8; ++i) S[i] = 0.f;
;         for (int j = 1; j < w; ++j) { const u32x4 uw = *(const u32x4*)(proj + (size_t)(r0 - j) * PW + C_U + 8 * lane); float u[8]; unpack8(uw, u);
; #pragma unroll
;             for (int i = 0; i < 8; ++i) S[i] += u[i]; }
.LBB0_221:
	s_movk_i32 s14, 0xdc00
	s_mov_b32 s15, -1
	s_mov_b64 s[40:41], exec
	v_cmp_le_u32_e64 s[34:35], 2, v50
	v_cmp_le_u32_e64 s[36:37], 4, v50
	v_cmp_le_u32_e64 s[38:39], 8, v50
	global_load_dwordx4 v[64:67], v[10:11], off
	v_lshl_add_u64 v[10:11], v[10:11], 0, s[14:15]
	s_mov_b64 exec, s[34:35]
	global_load_dwordx4 v[68:71], v[10:11], off
	v_lshl_add_u64 v[10:11], v[10:11], 0, s[14:15]
	global_load_dwordx4 v[72:75], v[10:11], off
	v_lshl_add_u64 v[10:11], v[10:11], 0, s[14:15]
	s_mov_b64 exec, s[36:37]
	global_load_dwordx4 v[76:79], v[10:11], off
	v_lshl_add_u64 v[10:11], v[10:11], 0, s[14:15]
	global_load_dwordx4 v[80:83], v[10:11], off
	v_lshl_add_u64 v[10:11], v[10:11], 0, s[14:15]
	global_load_dwordx4 v[84:87], v[10:11], off
	v_lshl_add_u64 v[10:11], v[10:11], 0, s[14:15]
	global_load_dwordx4 v[88:91], v[10:11], off
	v_lshl_add_u64 v[10:11], v[10:11], 0, s[14:15]
	s_mov_b64 exec, s[38:39]
	global_load_dwordx4 v[92:95], v[10:11], off
	v_lshl_add_u64 v[10:11], v[10:11], 0, s[14:15]
	global_load_dwordx4 v[96:99], v[10:11], off
	v_lshl_add_u64 v[10:11], v[10:11], 0, s[14:15]
	global_load_dwordx4 v[100:103], v[10:11], off
	v_lshl_add_u64 v[10:11], v[10:11], 0, s[14:15]
	global_load_dwordx4 v[104:107], v[10:11], off
	v_lshl_add_u64 v[10:11], v[10:11], 0, s[14:15]
	global_load_dwordx4 v[108:111], v[10:11], off
	v_lshl_add_u64 v[10:11], v[10:11], 0, s[14:15]
	global_load_dwordx4 v[112:115], v[10:11], off
	v_lshl_add_u64 v[10:11], v[10:11], 0, s[14:15]
	global_load_dwordx4 v[116:119], v[10:11], off
	v_lshl_add_u64 v[10:11], v[10:11], 0, s[14:15]
	global_load_dwordx4 v[120:123], v[10:11], off
	s_mov_b64 exec, s[40:41]
	s_waitcnt vmcnt(14)
	v_lshlrev_b32_e32 v12, 16, v64
	v_and_b32_e32 v13, 0xffff0000, v64
	v_lshlrev_b32_e32 v24, 16, v65
	v_and_b32_e32 v25, 0xffff0000, v65
	v_lshlrev_b32_e32 v34, 16, v66
	v_and_b32_e32 v35, 0xffff0000, v66
	v_lshlrev_b32_e32 v36, 16, v67
	v_and_b32_e32 v37, 0xffff0000, v67
	v_pk_add_f32 v[28:29], v[28:29], v[12:13]
	v_pk_add_f32 v[30:31], v[30:31], v[24:25]
	v_pk_add_f32 v[32:33], v[32:33], v[34:35]
	v_pk_add_f32 v[26:27], v[26:27], v[36:37]
	s_mov_b64 exec, s[34:35]
	s_waitcnt vmcnt(13)
	v_lshlrev_b32_e32 v12, 16, v68
	v_and_b32_e32 v13, 0xffff0000, v68
	v_lshlrev_b32_e32 v24, 16, v69
	v_and_b32_e32 v25, 0xffff0000, v69
	v_lshlrev_b32_e32 v34, 16, v70
	v_and_b32_e32 v35, 0xffff0000, v70
	v_lshlrev_b32_e32 v36, 16, v71
	v_and_b32_e32 v37, 0xffff0000, v71
	v_pk_add_f32 v[28:29], v[28:29], v[12:13]
	v_pk_add_f32 v[30:31], v[30:31], v[24:25]
	v_pk_add_f32 v[32:33], v[32:33], v[34:35]
	v_pk_add_f32 v[26:27], v[26:27], v[36:37]
	s_waitcnt vmcnt(12)
	v_lshlrev_b32_e32 v12, 16, v72
	v_and_b32_e32 v13, 0xffff0000, v72
	v_lshlrev_b32_e32 v24, 16, v73
	v_and_b32_e32 v25, 0xffff0000, v73
	v_lshlrev_b32_e32 v34, 16, v74
	v_and_b32_e32 v35, 0xffff0000, v74
	v_lshlrev_b32_e32 v36, 16, v75
	v_and_b32_e32 v37, 0xffff0000, v75
	v_pk_add_f32 v[28:29], v[28:29], v[12:13]
	v_pk_add_f32 v[30:31], v[30:31], v[24:25]
	v_pk_add_f32 v[32:33], v[32:33], v[34:35]
	v_pk_add_f32 v[26:27], v[26:27], v[36:37]
	s_mov_b64 exec, s[36:37]
	s_waitcnt vmcnt(11)
	v_lshlrev_b32_e32 v12, 16, v76
	v_and_b32_e32 v13, 0xffff0000, v76
	v_lshlrev_b32_e32 v24, 16, v77
	v_and_b32_e32 v25, 0xffff0000, v77
	v_lshlrev_b32_e32 v34, 16, v78
	v_and_b32_e32 v35, 0xffff0000, v78
	v_lshlrev_b32_e32 v36, 16, v79
	v_and_b32_e32 v37, 0xffff0000, v79
	v_pk_add_f32 v[28:29], v[28:29], v[12:13]
	v_pk_add_f32 v[30:31], v[30:31], v[24:25]
	v_pk_add_f32 v[32:33], v[32:33], v[34:35]
	v_pk_add_f32 v[26:27], v[26:27], v[36:37]
	s_waitcnt vmcnt(10)
	v_lshlrev_b32_e32 v12, 16, v80
	v_and_b32_e32 v13, 0xffff0000, v80
	v_lshlrev_b32_e32 v24, 16, v81
	v_and_b32_e32 v25, 0xffff0000, v81
	v_lshlrev_b32_e32 v34, 16, v82
	v_and_b32_e32 v35, 0xffff0000, v82
	v_lshlrev_b32_e32 v36, 16, v83
	v_and_b32_e32 v37, 0xffff0000, v83
	v_pk_add_f32 v[28:29], v[28:29], v[12:13]
	v_pk_add_f32 v[30:31], v[30:31], v[24:25]
	v_pk_add_f32 v[32:33], v[32:33], v[34:35]
	v_pk_add_f32 v[26:27], v[26:27], v[36:37]
	s_waitcnt vmcnt(9)
	v_lshlrev_b32_e32 v12, 16, v84
	v_and_b32_e32 v13, 0xffff0000, v84
	v_lshlrev_b32_e32 v24, 16, v85
	v_and_b32_e32 v25, 0xffff0000, v85
	v_lshlrev_b32_e32 v34, 16, v86
	v_and_b32_e32 v35, 0xffff0000, v86
	v_lshlrev_b32_e32 v36, 16, v87
	v_and_b32_e32 v37, 0xffff0000, v87
	v_pk_add_f32 v[28:29], v[28:29], v[12:13]
	v_pk_add_f32 v[30:31], v[30:31], v[24:25]
	v_pk_add_f32 v[32:33], v[32:33], v[34:35]
	v_pk_add_f32 v[26:27], v[26:27], v[36:37]
	s_waitcnt vmcnt(8)
	v_lshlrev_b32_e32 v12, 16, v88
	v_and_b32_e32 v13, 0xffff0000, v88
	v_lshlrev_b32_e32 v24, 16, v89
	v_and_b32_e32 v25, 0xffff0000, v89
	v_lshlrev_b32_e32 v34, 16, v90
	v_and_b32_e32 v35, 0xffff0000, v90
	v_lshlrev_b32_e32 v36, 16, v91
	v_and_b32_e32 v37, 0xffff0000, v91
	v_pk_add_f32 v[28:29], v[28:29], v[12:13]
	v_pk_add_f32 v[30:31], v[30:31], v[24:25]
	v_pk_add_f32 v[32:33], v[32:33], v[34:35]
	v_pk_add_f32 v[26:27], v[26:27], v[36:37]
	s_mov_b64 exec, s[38:39]
	s_waitcnt vmcnt(7)
	v_lshlrev_b32_e32 v12, 16, v92
	v_and_b32_e32 v13, 0xffff0000, v92
	v_lshlrev_b32_e32 v24, 16, v93
	v_and_b32_e32 v25, 0xffff0000, v93
	v_lshlrev_b32_e32 v34, 16, v94
	v_and_b32_e32 v35, 0xffff0000, v94
	v_lshlrev_b32_e32 v36, 16, v95
	v_and_b32_e32 v37, 0xffff0000, v95
	v_pk_add_f32 v[28:29], v[28:29], v[12:13]
	v_pk_add_f32 v[30:31], v[30:31], v[24:25]
	v_pk_add_f32 v[32:33], v[32:33], v[34:35]
	v_pk_add_f32 v[26:27], v[26:27], v[36:37]
	s_waitcnt vmcnt(6)
; __device__ __forceinline__ void unpack8(const u32x4& w, float (&v)[8]) { v[0] = bf_lo(w.x); v[1] = bf_hi(w.x); v[2] = bf_lo(w.y); v[3] = bf_hi(w.y); v[4] = bf_lo(w.z); v[5] = bf_hi(w.z); v[6] = bf_lo(w.w); v[7] = bf_hi(w.w); }
; __device__ __forceinline__ void phase_pool(const Args& a, int l, int vcu, int NGW, int wv) {
;     ...
; #pragma unroll
;         for (int i = 0; i < 8; ++i) S[i] = 0.f;
;         for (int j = 1; j < w; ++j) { const u32x4 uw = *(const u32x4*)(proj + (size_t)(r0 - j) * PW + C_U + 8 * lane); float u[8]; unpack8(uw, u);
; #pragma unroll
;             for (int i = 0; i < 8; ++i) S[i] += u[i]; }
; #pragma unroll 2
;         for (int i = 0; i < nrows; ++i) {
;             const int m = r0 + i, t = p0 + i - PADF;
;             bf16_t* prow = proj + (size_t)m * PW;
;             const u32x4 uw = *(const u32x4*)(prow + C_U + 8 * lane); float u[8]; unpack8(uw, u);
;             const u32x4 zw = *(const u32x4*)(prow + C_Z + 8 * lane); float z[8]; unpack8(zw, z);
;             const u32x4 ow = *(const u32x4*)(proj + (size_t)(m - (w - 1)) * PW + C_U + 8 * lane); float o[8]; unpack8(ow, o);
	v_lshlrev_b32_e32 v12, 16, v96
	v_and_b32_e32 v13, 0xffff0000, v96
	v_lshlrev_b32_e32 v24, 16, v97
	v_and_b32_e32 v25, 0xffff0000, v97
	v_lshlrev_b32_e32 v34, 16, v98
	v_and_b32_e32 v35, 0xffff0000, v98
	v_lshlrev_b32_e32 v36, 16, v99
	v_and_b32_e32 v37, 0xffff0000, v99
	v_pk_add_f32 v[28:29], v[28:29], v[12:13]
	v_pk_add_f32 v[30:31], v[30:31], v[24:25]
	v_pk_add_f32 v[32:33], v[32:33], v[34:35]
	v_pk_add_f32 v[26:27], v[26:27], v[36:37]
	s_waitcnt vmcnt(5)
	v_lshlrev_b32_e32 v12, 16, v100
	v_and_b32_e32 v13, 0xffff0000, v100
	v_lshlrev_b32_e32 v24, 16, v101
	v_and_b32_e32 v25, 0xffff0000, v101
	v_lshlrev_b32_e32 v34, 16, v102
	v_and_b32_e32 v35, 0xffff0000, v102
	v_lshlrev_b32_e32 v36, 16, v103
	v_and_b32_e32 v37, 0xffff0000, v103
	v_pk_add_f32 v[28:29], v[28:29], v[12:13]
	v_pk_add_f32 v[30:31], v[30:31], v[24:25]
	v_pk_add_f32 v[32:33], v[32:33], v[34:35]
	v_pk_add_f32 v[26:27], v[26:27], v[36:37]
	s_waitcnt vmcnt(4)
	v_lshlrev_b32_e32 v12, 16, v104
	v_and_b32_e32 v13, 0xffff0000, v104
	v_lshlrev_b32_e32 v24, 16, v105
	v_and_b32_e32 v25, 0xffff0000, v105
	v_lshlrev_b32_e32 v34, 16, v106
	v_and_b32_e32 v35, 0xffff0000, v106
	v_lshlrev_b32_e32 v36, 16, v107
	v_and_b32_e32 v37, 0xffff0000, v107
	v_pk_add_f32 v[28:29], v[28:29], v[12:13]
	v_pk_add_f32 v[30:31], v[30:31], v[24:25]
	v_pk_add_f32 v[32:33], v[32:33], v[34:35]
	v_pk_add_f32 v[26:27], v[26:27], v[36:37]
	s_waitcnt vmcnt(3)
	v_lshlrev_b32_e32 v12, 16, v108
	v_and_b32_e32 v13, 0xffff0000, v108
	v_lshlrev_b32_e32 v24, 16, v109
	v_and_b32_e32 v25, 0xffff0000, v109
	v_lshlrev_b32_e32 v34, 16, v110
	v_and_b32_e32 v35, 0xffff0000, v110
	v_lshlrev_b32_e32 v36, 16, v111
	v_and_b32_e32 v37, 0xffff0000, v111
	v_pk_add_f32 v[28:29], v[28:29], v[12:13]
	v_pk_add_f32 v[30:31], v[30:31], v[24:25]
	v_pk_add_f32 v[32:33], v[32:33], v[34:35]
	v_pk_add_f32 v[26:27], v[26:27], v[36:37]
	s_waitcnt vmcnt(2)
	v_lshlrev_b32_e32 v12, 16, v112
	v_and_b32_e32 v13, 0xffff0000, v112
	v_lshlrev_b32_e32 v24, 16, v113
	v_and_b32_e32 v25, 0xffff0000, v113
	v_lshlrev_b32_e32 v34, 16, v114
	v_and_b32_e32 v35, 0xffff0000, v114
	v_lshlrev_b32_e32 v36, 16, v115
	v_and_b32_e32 v37, 0xffff0000, v115
	v_pk_add_f32 v[28:29], v[28:29], v[12:13]
	v_pk_add_f32 v[30:31], v[30:31], v[24:25]
	v_pk_add_f32 v[32:33], v[32:33], v[34:35]
	v_pk_add_f32 v[26:27], v[26:27], v[36:37]
	s_waitcnt vmcnt(1)
	v_lshlrev_b32_e32 v12, 16, v116
	v_and_b32_e32 v13, 0xffff0000, v116
	v_lshlrev_b32_e32 v24, 16, v117
	v_and_b32_e32 v25, 0xffff0000, v117
	v_lshlrev_b32_e32 v34, 16, v118
	v_and_b32_e32 v35, 0xffff0000, v118
	v_lshlrev_b32_e32 v36, 16, v119
	v_and_b32_e32 v37, 0xffff0000, v119
	v_pk_add_f32 v[28:29], v[28:29], v[12:13]
	v_pk_add_f32 v[30:31], v[30:31], v[24:25]
	v_pk_add_f32 v[32:33], v[32:33], v[34:35]
	v_pk_add_f32 v[26:27], v[26:27], v[36:37]
	s_waitcnt vmcnt(0)
	v_lshlrev_b32_e32 v12, 16, v120
	v_and_b32_e32 v13, 0xffff0000, v120
	v_lshlrev_b32_e32 v24, 16, v121
	v_and_b32_e32 v25, 0xffff0000, v121
	v_lshlrev_b32_e32 v34, 16, v122
	v_and_b32_e32 v35, 0xffff0000, v122
	v_lshlrev_b32_e32 v36, 16, v123
	v_and_b32_e32 v37, 0xffff0000, v123
	v_pk_add_f32 v[28:29], v[28:29], v[12:13]
	v_pk_add_f32 v[30:31], v[30:31], v[24:25]
	v_pk_add_f32 v[32:33], v[32:33], v[34:35]
	v_pk_add_f32 v[26:27], v[26:27], v[36:37]
	s_mov_b64 exec, s[40:41]
	s_cmpk_gt_u32 s12, 0x1e9
	s_cbranch_scc1 .LBB0_227
	s_mul_i32 s0, s5, 0x208a
	s_add_i32 s1, s3, s0
	v_med3_i32 v5, s1, 1, 17
	s_sub_i32 s0, s4, s0
	v_subrev_u32_e32 v9, s6, v0
	s_mov_b32 s1, 0
	s_nop 0
	v_readfirstlane_b32 s14, v5
	s_add_i32 s16, s14, -1
	s_min_u32 s15, 0, s16
	s_add_i32 s12, s7, s15
	v_mad_i64_i32 v[112:113], s[44:45], s12, v233, v[14:15]
	global_load_dwordx4 v[64:67], v[112:113], off
	v_add_u32_e32 v114, s15, v9
	v_mad_i64_i32 v[114:115], s[44:45], v114, s29, v[14:15]
	global_load_dwordx4 v[68:71], v[114:115], off
	global_load_dwordx4 v[72:75], v[112:113], off offset:1024
	global_load_dword v116, v[112:113], off
	s_min_u32 s15, 1, s16
	s_add_i32 s12, s7, s15
	v_mad_i64_i32 v[112:113], s[44:45], s12, v233, v[14:15]
	global_load_dwordx4 v[76:79], v[112:113], off
	v_add_u32_e32 v114, s15, v9
	v_mad_i64_i32 v[114:115], s[44:45], v114, s29, v[14:15]
	global_load_dwordx4 v[80:83], v[114:115], off
	global_load_dwordx4 v[84:87], v[112:113], off offset:1024
	global_load_dword v116, v[112:113], off
	s_min_u32 s15, 2, s16
	s_add_i32 s12, s7, s15
	v_mad_i64_i32 v[112:113], s[44:45], s12, v233, v[14:15]
	global_load_dwordx4 v[88:91], v[112:113], off
	v_add_u32_e32 v114, s15, v9
	v_mad_i64_i32 v[114:115], s[44:45], v114, s29, v[14:15]
	global_load_dwordx4 v[92:95], v[114:115], off
	global_load_dwordx4 v[96:99], v[112:113], off offset:1024
	global_load_dword v116, v[112:113], off
	s_min_u32 s15, 3, s16
	s_add_i32 s12, s7, s15
	v_mad_i64_i32 v[112:113], s[44:45], s12, v233, v[14:15]
	global_load_dwordx4 v[100:103], v[112:113], off
	v_add_u32_e32 v114, s15, v9
	v_mad_i64_i32 v[114:115], s[44:45], v114, s29, v[14:15]
	global_load_dwordx4 v[104:107], v[114:115], off
	global_load_dwordx4 v[108:111], v[112:113], off offset:1024
	global_load_dword v116, v[112:113], off
	s_branch .Lpool_u0
; __device__ __forceinline__ float siluf_(float z) { return z * sigmoidf_(z); }
; __device__ __forceinline__ void unpack8(const u32x4& w, float (&v)[8]) { v[0] = bf_lo(w.x); v[1] = bf_hi(w.x); v[2] = bf_lo(w.y); v[3] = bf_hi(w.y); v[4] = bf_lo(w.z); v[5] = bf_hi(w.z); v[6] = bf_lo(w.w); v[7] = bf_hi(w.w); }
; __device__ __forceinline__ void phase_pool(const Args& a, int l, int vcu, int NGW, int wv) {
;     ...
;         for (int i = 0; i < nrows; ++i) {
;             const int m = r0 + i, t = p0 + i - PADF;
;             bf16_t* prow = proj + (size_t)m * PW;
;             const u32x4 uw = *(const u32x4*)(prow + C_U + 8 * lane); float u[8]; unpack8(uw, u);
;             const u32x4 zw = *(const u32x4*)(prow + C_Z + 8 * lane); float z[8]; unpack8(zw, z);
;             const u32x4 ow = *(const u32x4*)(proj + (size_t)(m - (w - 1)) * PW + C_U + 8 * lane); float o[8]; unpack8(ow, o);
; #pragma unroll
;             for (int k = 0; k < 8; ++k) S[k] += u[k];
;             f32x4 r0v = (f32x4){0.f, 0.f, 0.f, 0.f}, r1v = r0v;
;             if (t >= 0) { const int cnt = (t + 1 < w) ? (t + 1) : w; const float ic = 1.0f / (float)cnt;
; #pragma unroll
;                 for (int k = 0; k < 4; ++k) { r0v[k] = (S[k] * ic - u[k]) * sc0[k] * siluf_(z[k]); r1v[k] = (S[4 + k] * ic - u[4 + k]) * sc1[k] * siluf_(z[4 + k]); } }
.Lpool_u0:
	s_waitcnt vmcnt(13)
	s_add_i32 s12, s7, s1
	v_mad_i64_i32 v[24:25], s[12:13], s12, v233, v[14:15]
	v_mov_b32_e32 v52, v64
	v_mov_b32_e32 v53, v65
	v_mov_b32_e32 v54, v66
	v_mov_b32_e32 v55, v67
	v_mov_b32_e32 v10, v68
	v_mov_b32_e32 v11, v69
	v_mov_b32_e32 v12, v70
	v_mov_b32_e32 v13, v71
	v_mov_b32_e32 v120, v72
	v_mov_b32_e32 v121, v73
	v_mov_b32_e32 v122, v74
	v_mov_b32_e32 v123, v75
	s_add_i32 s15, s1, 4
	s_min_u32 s15, s15, s16
	s_add_i32 s12, s7, s15
	v_mad_i64_i32 v[112:113], s[44:45], s12, v233, v[14:15]
	global_load_dwordx4 v[64:67], v[112:113], off
	v_add_u32_e32 v114, s15, v9
	v_mad_i64_i32 v[114:115], s[44:45], v114, s29, v[14:15]
	global_load_dwordx4 v[68:71], v[114:115], off
	global_load_dwordx4 v[72:75], v[112:113], off offset:1024
	s_add_i32 s12, s0, s1
	v_mov_b32_e32 v38, 0
	v_mov_b32_e32 v39, 0
	v_mov_b32_e32 v40, 0
	v_mov_b32_e32 v41, 0
	v_mov_b32_e32 v42, 0
	v_mov_b32_e32 v43, 0
	v_mov_b32_e32 v46, 0
	s_cmpk_lt_i32 s12, 0x70
	v_mov_b32_e32 v47, 0
	v_lshlrev_b32_e32 v48, 16, v52
	v_and_b32_e32 v49, 0xffff0000, v52
	v_lshlrev_b32_e32 v36, 16, v53
	v_and_b32_e32 v37, 0xffff0000, v53
	v_lshlrev_b32_e32 v44, 16, v54
	v_and_b32_e32 v45, 0xffff0000, v54
	v_lshlrev_b32_e32 v34, 16, v55
	v_and_b32_e32 v35, 0xffff0000, v55
	v_pk_add_f32 v[28:29], v[28:29], v[48:49]
	v_pk_add_f32 v[30:31], v[30:31], v[36:37]
	v_pk_add_f32 v[32:33], v[32:33], v[44:45]
	v_pk_add_f32 v[26:27], v[26:27], v[34:35]
	s_cbranch_scc1 .Lpool_t0
	v_mov_b32_e32 v38, v120
	v_mov_b32_e32 v39, v121
	v_mov_b32_e32 v40, v122
	v_mov_b32_e32 v41, v123
	s_addk_i32 s12, 0xff91
	v_min_i32_e32 v21, s12, v17
	v_cvt_f32_u32_e32 v21, v21
	v_div_scale_f32 v23, s[12:13], v21, v21, 1.0
	v_rcp_f32_e32 v42, v23
	v_div_scale_f32 v43, vcc, 1.0, v21, 1.0
	v_fma_f32 v46, -v23, v42, 1.0
	v_fmac_f32_e32 v42, v46, v42
	v_mul_f32_e32 v46, v43, v42
	v_fma_f32 v47, -v23, v46, v43
	v_fmac_f32_e32 v46, v47, v42
	v_fma_f32 v23, -v23, v46, v43
	v_div_fmas_f32 v23, v23, v42, v46
	v_div_fixup_f32 v42, v23, v21, 1.0
	v_pk_fma_f32 v[46:47], v[42:43], v[28:29], v[48:49] op_sel_hi:[0,1,1] neg_lo:[0,0,1] neg_hi:[0,0,1]
	v_fma_f32 v21, v42, v30, -v36
	v_fma_f32 v23, v42, v26, -v34
	v_fma_f32 v34, v42, v31, -v37
	v_fma_f32 v36, v42, v27, -v35
	v_pk_fma_f32 v[44:45], v[42:43], v[32:33], v[44:45] op_sel_hi:[0,1,1] neg_lo:[0,0,1] neg_hi:[0,0,1]
	v_pk_mul_f32 v[42:43], v[2:3], v[46:47]
	v_mul_f32_e32 v46, v4, v21
	v_mul_f32_e32 v48, v8, v23
	v_pk_mul_f32 v[44:45], v[6:7], v[44:45]
	v_and_b32_e32 v35, 0xffff0000, v39
	v_and_b32_e32 v37, 0xffff0000, v41
	v_lshlrev_b32_e32 v52, 16, v38
	v_and_b32_e32 v53, 0xffff0000, v38
	v_lshlrev_b32_e32 v47, 16, v39
	v_lshlrev_b32_e32 v49, 16, v41
	v_lshlrev_b32_e32 v38, 16, v40
	v_and_b32_e32 v39, 0xffff0000, v40
	v_mul_f32_e32 v21, 0xbfb8aa3b, v52
	v_mul_f32_e32 v23, 0xbfb8aa3b, v53
	v_mul_f32_e32 v55, 0xbfb8aa3b, v35
	v_mul_f32_e32 v56, 0xbfb8aa3b, v37
	v_mul_f32_e32 v40, 0xbfb8aa3b, v38
	v_mul_f32_e32 v41, 0xbfb8aa3b, v39
	v_mul_f32_e32 v51, 0xbfb8aa3b, v47
	v_mul_f32_e32 v54, 0xbfb8aa3b, v49
	v_exp_f32_e32 v21, v21
	v_exp_f32_e32 v23, v23
	v_exp_f32_e32 v55, v55
	v_exp_f32_e32 v56, v56
	v_exp_f32_e32 v40, v40
	v_exp_f32_e32 v41, v41
	v_exp_f32_e32 v51, v51
	v_exp_f32_e32 v54, v54
	v_add_f32_e32 v21, 1.0, v21
	v_add_f32_e32 v23, 1.0, v23
	v_add_f32_e32 v60, 1.0, v55
	v_add_f32_e32 v56, 1.0, v56
	v_add_f32_e32 v57, 1.0, v40
	v_add_f32_e32 v58, 1.0, v41
	v_add_f32_e32 v51, 1.0, v51
	v_add_f32_e32 v59, 1.0, v54
	v_rcp_f32_e32 v40, v21
	v_rcp_f32_e32 v41, v23
	v_rcp_f32_e32 v21, v60
	v_rcp_f32_e32 v23, v56
	v_rcp_f32_e32 v54, v57
	v_rcp_f32_e32 v55, v58
	v_rcp_f32_e32 v51, v51
	v_rcp_f32_e32 v57, v59
	v_pk_mul_f32 v[34:35], v[20:21], v[34:35]
	v_pk_mul_f32 v[36:37], v[22:23], v[36:37]
	v_pk_mul_f32 v[40:41], v[40:41], v[52:53]
	v_pk_mul_f32 v[52:53], v[54:55], v[38:39]
	v_mul_f32_e32 v54, v51, v47
	v_mul_f32_e32 v56, v57, v49
	v_mov_b32_e32 v47, v34
	v_mov_b32_e32 v55, v35
	v_mov_b32_e32 v49, v36
	v_mov_b32_e32 v57, v37
	v_pk_mul_f32 v[38:39], v[42:43], v[40:41]
	v_pk_mul_f32 v[42:43], v[44:45], v[52:53]
	v_pk_mul_f32 v[40:41], v[46:47], v[54:55]
	v_pk_mul_f32 v[46:47], v[48:49], v[56:57]

; __device__ __forceinline__ float siluf_(float z) { return z * sigmoidf_(z); }
; __device__ __forceinline__ void unpack8(const u32x4& w, float (&v)[8]) { v[0] = bf_lo(w.x); v[1] = bf_hi(w.x); v[2] = bf_lo(w.y); v[3] = bf_hi(w.y); v[4] = bf_lo(w.z); v[5] = bf_hi(w.z); v[6] = bf_lo(w.w); v[7] = bf_hi(w.w); }
; __device__ __forceinline__ void phase_pool(const Args& a, int l, int vcu, int NGW, int wv) {
;     ...
;         for (int i = 0; i < nrows; ++i) {
;             const int m = r0 + i, t = p0 + i - PADF;
;             bf16_t* prow = proj + (size_t)m * PW;
;             const u32x4 uw = *(const u32x4*)(prow + C_U + 8 * lane); float u[8]; unpack8(uw, u);
;             const u32x4 zw = *(const u32x4*)(prow + C_Z + 8 * lane); float z[8]; unpack8(zw, z);
;             const u32x4 ow = *(const u32x4*)(proj + (size_t)(m - (w - 1)) * PW + C_U + 8 * lane); float o[8]; unpack8(ow, o);
; #pragma unroll
;             for (int k = 0; k < 8; ++k) S[k] += u[k];
;             f32x4 r0v = (f32x4){0.f, 0.f, 0.f, 0.f}, r1v = r0v;
;             if (t >= 0) { const int cnt = (t + 1 < w) ? (t + 1) : w; const float ic = 1.0f / (float)cnt;
; #pragma unroll
;                 for (int k = 0; k < 4; ++k) { r0v[k] = (S[k] * ic - u[k]) * sc0[k] * siluf_(z[k]); r1v[k] = (S[4 + k] * ic - u[4 + k]) * sc1[k] * siluf_(z[4 + k]); } }
.Lpool_u1:
	s_waitcnt vmcnt(13)
	s_add_i32 s12, s7, s1
	v_mad_i64_i32 v[24:25], s[12:13], s12, v233, v[14:15]
	v_mov_b32_e32 v52, v76
	v_mov_b32_e32 v53, v77
	v_mov_b32_e32 v54, v78
	v_mov_b32_e32 v55, v79
	v_mov_b32_e32 v10, v80
	v_mov_b32_e32 v11, v81
	v_mov_b32_e32 v12, v82
	v_mov_b32_e32 v13, v83
	v_mov_b32_e32 v120, v84
	v_mov_b32_e32 v121, v85
	v_mov_b32_e32 v122, v86
	v_mov_b32_e32 v123, v87
	s_add_i32 s15, s1, 4
	s_min_u32 s15, s15, s16
	s_add_i32 s12, s7, s15
	v_mad_i64_i32 v[112:113], s[44:45], s12, v233, v[14:15]
	global_load_dwordx4 v[76:79], v[112:113], off
	v_add_u32_e32 v114, s15, v9
	v_mad_i64_i32 v[114:115], s[44:45], v114, s29, v[14:15]
	global_load_dwordx4 v[80:83], v[114:115], off
	global_load_dwordx4 v[84:87], v[112:113], off offset:1024
	s_add_i32 s12, s0, s1
	v_mov_b32_e32 v38, 0
	v_mov_b32_e32 v39, 0
	v_mov_b32_e32 v40, 0
	v_mov_b32_e32 v41, 0
	v_mov_b32_e32 v42, 0
	v_mov_b32_e32 v43, 0
	v_mov_b32_e32 v46, 0
	s_cmpk_lt_i32 s12, 0x70
	v_mov_b32_e32 v47, 0
	v_lshlrev_b32_e32 v48, 16, v52
	v_and_b32_e32 v49, 0xffff0000, v52
	v_lshlrev_b32_e32 v36, 16, v53
	v_and_b32_e32 v37, 0xffff0000, v53
	v_lshlrev_b32_e32 v44, 16, v54
	v_and_b32_e32 v45, 0xffff0000, v54
	v_lshlrev_b32_e32 v34, 16, v55
	v_and_b32_e32 v35, 0xffff0000, v55
	v_pk_add_f32 v[28:29], v[28:29], v[48:49]
	v_pk_add_f32 v[30:31], v[30:31], v[36:37]
	v_pk_add_f32 v[32:33], v[32:33], v[44:45]
	v_pk_add_f32 v[26:27], v[26:27], v[34:35]
	s_cbranch_scc1 .Lpool_t1
	v_mov_b32_e32 v38, v120
	v_mov_b32_e32 v39, v121
	v_mov_b32_e32 v40, v122
	v_mov_b32_e32 v41, v123
	s_addk_i32 s12, 0xff91
	v_min_i32_e32 v21, s12, v17
	v_cvt_f32_u32_e32 v21, v21
	v_div_scale_f32 v23, s[12:13], v21, v21, 1.0
	v_rcp_f32_e32 v42, v23
	v_div_scale_f32 v43, vcc, 1.0, v21, 1.0
	v_fma_f32 v46, -v23, v42, 1.0
	v_fmac_f32_e32 v42, v46, v42
	v_mul_f32_e32 v46, v43, v42
	v_fma_f32 v47, -v23, v46, v43
	v_fmac_f32_e32 v46, v47, v42
	v_fma_f32 v23, -v23, v46, v43
	v_div_fmas_f32 v23, v23, v42, v46
	v_div_fixup_f32 v42, v23, v21, 1.0
	v_pk_fma_f32 v[46:47], v[42:43], v[28:29], v[48:49] op_sel_hi:[0,1,1] neg_lo:[0,0,1] neg_hi:[0,0,1]
	v_fma_f32 v21, v42, v30, -v36
	v_fma_f32 v23, v42, v26, -v34
	v_fma_f32 v34, v42, v31, -v37
	v_fma_f32 v36, v42, v27, -v35
	v_pk_fma_f32 v[44:45], v[42:43], v[32:33], v[44:45] op_sel_hi:[0,1,1] neg_lo:[0,0,1] neg_hi:[0,0,1]
	v_pk_mul_f32 v[42:43], v[2:3], v[46:47]
	v_mul_f32_e32 v46, v4, v21
	v_mul_f32_e32 v48, v8, v23
	v_pk_mul_f32 v[44:45], v[6:7], v[44:45]
	v_and_b32_e32 v35, 0xffff0000, v39
	v_and_b32_e32 v37, 0xffff0000, v41
	v_lshlrev_b32_e32 v52, 16, v38
	v_and_b32_e32 v53, 0xffff0000, v38
	v_lshlrev_b32_e32 v47, 16, v39
	v_lshlrev_b32_e32 v49, 16, v41
	v_lshlrev_b32_e32 v38, 16, v40
	v_and_b32_e32 v39, 0xffff0000, v40
	v_mul_f32_e32 v21, 0xbfb8aa3b, v52
	v_mul_f32_e32 v23, 0xbfb8aa3b, v53
	v_mul_f32_e32 v55, 0xbfb8aa3b, v35
	v_mul_f32_e32 v56, 0xbfb8aa3b, v37
	v_mul_f32_e32 v40, 0xbfb8aa3b, v38
	v_mul_f32_e32 v41, 0xbfb8aa3b, v39
	v_mul_f32_e32 v51, 0xbfb8aa3b, v47
	v_mul_f32_e32 v54, 0xbfb8aa3b, v49
	v_exp_f32_e32 v21, v21
	v_exp_f32_e32 v23, v23
	v_exp_f32_e32 v55, v55
	v_exp_f32_e32 v56, v56
	v_exp_f32_e32 v40, v40
	v_exp_f32_e32 v41, v41
	v_exp_f32_e32 v51, v51
	v_exp_f32_e32 v54, v54
	v_add_f32_e32 v21, 1.0, v21
	v_add_f32_e32 v23, 1.0, v23
	v_add_f32_e32 v60, 1.0, v55
	v_add_f32_e32 v56, 1.0, v56
	v_add_f32_e32 v57, 1.0, v40
	v_add_f32_e32 v58, 1.0, v41
	v_add_f32_e32 v51, 1.0, v51
	v_add_f32_e32 v59, 1.0, v54
	v_rcp_f32_e32 v40, v21
	v_rcp_f32_e32 v41, v23
	v_rcp_f32_e32 v21, v60
	v_rcp_f32_e32 v23, v56
	v_rcp_f32_e32 v54, v57
	v_rcp_f32_e32 v55, v58
	v_rcp_f32_e32 v51, v51
	v_rcp_f32_e32 v57, v59
	v_pk_mul_f32 v[34:35], v[20:21], v[34:35]
	v_pk_mul_f32 v[36:37], v[22:23], v[36:37]
	v_pk_mul_f32 v[40:41], v[40:41], v[52:53]
	v_pk_mul_f32 v[52:53], v[54:55], v[38:39]
	v_mul_f32_e32 v54, v51, v47
	v_mul_f32_e32 v56, v57, v49
	v_mov_b32_e32 v47, v34
	v_mov_b32_e32 v55, v35
	v_mov_b32_e32 v49, v36
	v_mov_b32_e32 v57, v37
	v_pk_mul_f32 v[38:39], v[42:43], v[40:41]
	v_pk_mul_f32 v[42:43], v[44:45], v[52:53]
	v_pk_mul_f32 v[40:41], v[46:47], v[54:55]
	v_pk_mul_f32 v[46:47], v[48:49], v[56:57]

; __device__ __forceinline__ float siluf_(float z) { return z * sigmoidf_(z); }
; __device__ __forceinline__ void unpack8(const u32x4& w, float (&v)[8]) { v[0] = bf_lo(w.x); v[1] = bf_hi(w.x); v[2] = bf_lo(w.y); v[3] = bf_hi(w.y); v[4] = bf_lo(w.z); v[5] = bf_hi(w.z); v[6] = bf_lo(w.w); v[7] = bf_hi(w.w); }
; __device__ __forceinline__ void phase_pool(const Args& a, int l, int vcu, int NGW, int wv) {
;     ...
;         for (int i = 0; i < nrows; ++i) {
;             const int m = r0 + i, t = p0 + i - PADF;
;             bf16_t* prow = proj + (size_t)m * PW;
;             const u32x4 uw = *(const u32x4*)(prow + C_U + 8 * lane); float u[8]; unpack8(uw, u);
;             const u32x4 zw = *(const u32x4*)(prow + C_Z + 8 * lane); float z[8]; unpack8(zw, z);
;             const u32x4 ow = *(const u32x4*)(proj + (size_t)(m - (w - 1)) * PW + C_U + 8 * lane); float o[8]; unpack8(ow, o);
; #pragma unroll
;             for (int k = 0; k < 8; ++k) S[k] += u[k];
;             f32x4 r0v = (f32x4){0.f, 0.f, 0.f, 0.f}, r1v = r0v;
;             if (t >= 0) { const int cnt = (t + 1 < w) ? (t + 1) : w; const float ic = 1.0f / (float)cnt;
; #pragma unroll
;                 for (int k = 0; k < 4; ++k) { r0v[k] = (S[k] * ic - u[k]) * sc0[k] * siluf_(z[k]); r1v[k] = (S[4 + k] * ic - u[4 + k]) * sc1[k] * siluf_(z[4 + k]); } }
.Lpool_u2:
	s_waitcnt vmcnt(13)
	s_add_i32 s12, s7, s1
	v_mad_i64_i32 v[24:25], s[12:13], s12, v233, v[14:15]
	v_mov_b32_e32 v52, v88
	v_mov_b32_e32 v53, v89
	v_mov_b32_e32 v54, v90
	v_mov_b32_e32 v55, v91
	v_mov_b32_e32 v10, v92
	v_mov_b32_e32 v11, v93
	v_mov_b32_e32 v12, v94
	v_mov_b32_e32 v13, v95
	v_mov_b32_e32 v120, v96
	v_mov_b32_e32 v121, v97
	v_mov_b32_e32 v122, v98
	v_mov_b32_e32 v123, v99
	s_add_i32 s15, s1, 4
	s_min_u32 s15, s15, s16
	s_add_i32 s12, s7, s15
	v_mad_i64_i32 v[112:113], s[44:45], s12, v233, v[14:15]
	global_load_dwordx4 v[88:91], v[112:113], off
	v_add_u32_e32 v114, s15, v9
	v_mad_i64_i32 v[114:115], s[44:45], v114, s29, v[14:15]
	global_load_dwordx4 v[92:95], v[114:115], off
	global_load_dwordx4 v[96:99], v[112:113], off offset:1024
	s_add_i32 s12, s0, s1
	v_mov_b32_e32 v38, 0
	v_mov_b32_e32 v39, 0
	v_mov_b32_e32 v40, 0
	v_mov_b32_e32 v41, 0
	v_mov_b32_e32 v42, 0
	v_mov_b32_e32 v43, 0
	v_mov_b32_e32 v46, 0
	s_cmpk_lt_i32 s12, 0x70
	v_mov_b32_e32 v47, 0
	v_lshlrev_b32_e32 v48, 16, v52
	v_and_b32_e32 v49, 0xffff0000, v52
	v_lshlrev_b32_e32 v36, 16, v53
	v_and_b32_e32 v37, 0xffff0000, v53
	v_lshlrev_b32_e32 v44, 16, v54
	v_and_b32_e32 v45, 0xffff0000, v54
	v_lshlrev_b32_e32 v34, 16, v55
	v_and_b32_e32 v35, 0xffff0000, v55
	v_pk_add_f32 v[28:29], v[28:29], v[48:49]
	v_pk_add_f32 v[30:31], v[30:31], v[36:37]
	v_pk_add_f32 v[32:33], v[32:33], v[44:45]
	v_pk_add_f32 v[26:27], v[26:27], v[34:35]
	s_cbranch_scc1 .Lpool_t2
	v_mov_b32_e32 v38, v120
	v_mov_b32_e32 v39, v121
	v_mov_b32_e32 v40, v122
	v_mov_b32_e32 v41, v123
	s_addk_i32 s12, 0xff91
	v_min_i32_e32 v21, s12, v17
	v_cvt_f32_u32_e32 v21, v21
	v_div_scale_f32 v23, s[12:13], v21, v21, 1.0
	v_rcp_f32_e32 v42, v23
	v_div_scale_f32 v43, vcc, 1.0, v21, 1.0
	v_fma_f32 v46, -v23, v42, 1.0
	v_fmac_f32_e32 v42, v46, v42
	v_mul_f32_e32 v46, v43, v42
	v_fma_f32 v47, -v23, v46, v43
	v_fmac_f32_e32 v46, v47, v42
	v_fma_f32 v23, -v23, v46, v43
	v_div_fmas_f32 v23, v23, v42, v46
	v_div_fixup_f32 v42, v23, v21, 1.0
	v_pk_fma_f32 v[46:47], v[42:43], v[28:29], v[48:49] op_sel_hi:[0,1,1] neg_lo:[0,0,1] neg_hi:[0,0,1]
	v_fma_f32 v21, v42, v30, -v36
	v_fma_f32 v23, v42, v26, -v34
	v_fma_f32 v34, v42, v31, -v37
	v_fma_f32 v36, v42, v27, -v35
	v_pk_fma_f32 v[44:45], v[42:43], v[32:33], v[44:45] op_sel_hi:[0,1,1] neg_lo:[0,0,1] neg_hi:[0,0,1]
	v_pk_mul_f32 v[42:43], v[2:3], v[46:47]
	v_mul_f32_e32 v46, v4, v21
	v_mul_f32_e32 v48, v8, v23
	v_pk_mul_f32 v[44:45], v[6:7], v[44:45]
	v_and_b32_e32 v35, 0xffff0000, v39
	v_and_b32_e32 v37, 0xffff0000, v41
	v_lshlrev_b32_e32 v52, 16, v38
	v_and_b32_e32 v53, 0xffff0000, v38
	v_lshlrev_b32_e32 v47, 16, v39
	v_lshlrev_b32_e32 v49, 16, v41
	v_lshlrev_b32_e32 v38, 16, v40
	v_and_b32_e32 v39, 0xffff0000, v40
	v_mul_f32_e32 v21, 0xbfb8aa3b, v52
	v_mul_f32_e32 v23, 0xbfb8aa3b, v53
	v_mul_f32_e32 v55, 0xbfb8aa3b, v35
	v_mul_f32_e32 v56, 0xbfb8aa3b, v37
	v_mul_f32_e32 v40, 0xbfb8aa3b, v38
	v_mul_f32_e32 v41, 0xbfb8aa3b, v39
	v_mul_f32_e32 v51, 0xbfb8aa3b, v47
	v_mul_f32_e32 v54, 0xbfb8aa3b, v49
	v_exp_f32_e32 v21, v21
	v_exp_f32_e32 v23, v23
	v_exp_f32_e32 v55, v55
	v_exp_f32_e32 v56, v56
	v_exp_f32_e32 v40, v40
	v_exp_f32_e32 v41, v41
	v_exp_f32_e32 v51, v51
	v_exp_f32_e32 v54, v54
	v_add_f32_e32 v21, 1.0, v21
	v_add_f32_e32 v23, 1.0, v23
	v_add_f32_e32 v60, 1.0, v55
	v_add_f32_e32 v56, 1.0, v56
	v_add_f32_e32 v57, 1.0, v40
	v_add_f32_e32 v58, 1.0, v41
	v_add_f32_e32 v51, 1.0, v51
	v_add_f32_e32 v59, 1.0, v54
	v_rcp_f32_e32 v40, v21
	v_rcp_f32_e32 v41, v23
	v_rcp_f32_e32 v21, v60
	v_rcp_f32_e32 v23, v56
	v_rcp_f32_e32 v54, v57
	v_rcp_f32_e32 v55, v58
	v_rcp_f32_e32 v51, v51
	v_rcp_f32_e32 v57, v59
	v_pk_mul_f32 v[34:35], v[20:21], v[34:35]
	v_pk_mul_f32 v[36:37], v[22:23], v[36:37]
	v_pk_mul_f32 v[40:41], v[40:41], v[52:53]
	v_pk_mul_f32 v[52:53], v[54:55], v[38:39]
	v_mul_f32_e32 v54, v51, v47
	v_mul_f32_e32 v56, v57, v49
	v_mov_b32_e32 v47, v34
	v_mov_b32_e32 v55, v35
	v_mov_b32_e32 v49, v36
	v_mov_b32_e32 v57, v37
	v_pk_mul_f32 v[38:39], v[42:43], v[40:41]
	v_pk_mul_f32 v[42:43], v[44:45], v[52:53]
	v_pk_mul_f32 v[40:41], v[46:47], v[54:55]
	v_pk_mul_f32 v[46:47], v[48:49], v[56:57]

; __device__ __forceinline__ float siluf_(float z) { return z * sigmoidf_(z); }
; __device__ __forceinline__ u32x4 pack8(const f32x4& a, const f32x4& b) { u32x4 w; w.x = cvt_pk_bf16(a[0], a[1]); w.y = cvt_pk_bf16(a[2], a[3]); w.z = cvt_pk_bf16(b[0], b[1]); w.w = cvt_pk_bf16(b[2], b[3]); return w; }
; __device__ __forceinline__ void unpack8(const u32x4& w, float (&v)[8]) { v[0] = bf_lo(w.x); v[1] = bf_hi(w.x); v[2] = bf_lo(w.y); v[3] = bf_hi(w.y); v[4] = bf_lo(w.z); v[5] = bf_hi(w.z); v[6] = bf_lo(w.w); v[7] = bf_hi(w.w); }
; __device__ __forceinline__ void phase_pool(const Args& a, int l, int vcu, int NGW, int wv) {
;     ...
;         for (int i = 0; i < nrows; ++i) {
;             const int m = r0 + i, t = p0 + i - PADF;
;             bf16_t* prow = proj + (size_t)m * PW;
;             const u32x4 uw = *(const u32x4*)(prow + C_U + 8 * lane); float u[8]; unpack8(uw, u);
;             const u32x4 zw = *(const u32x4*)(prow + C_Z + 8 * lane); float z[8]; unpack8(zw, z);
;             const u32x4 ow = *(const u32x4*)(proj + (size_t)(m - (w - 1)) * PW + C_U + 8 * lane); float o[8]; unpack8(ow, o);
; #pragma unroll
;             for (int k = 0; k < 8; ++k) S[k] += u[k];
;             f32x4 r0v = (f32x4){0.f, 0.f, 0.f, 0.f}, r1v = r0v;
;             if (t >= 0) { const int cnt = (t + 1 < w) ? (t + 1) : w; const float ic = 1.0f / (float)cnt;
; #pragma unroll
;                 for (int k = 0; k < 4; ++k) { r0v[k] = (S[k] * ic - u[k]) * sc0[k] * siluf_(z[k]); r1v[k] = (S[4 + k] * ic - u[4 + k]) * sc1[k] * siluf_(z[4 + k]); } }
;             *(u32x4*)(prow + C_P1Y + 8 * lane) = pack8(r0v, r1v);
; #pragma unroll
;             for (int k = 0; k < 8; ++k) S[k] -= o[k];
.Lpool_u3:
	s_waitcnt vmcnt(13)
	s_add_i32 s12, s7, s1
	v_mad_i64_i32 v[24:25], s[12:13], s12, v233, v[14:15]
	v_mov_b32_e32 v52, v100
	v_mov_b32_e32 v53, v101
	v_mov_b32_e32 v54, v102
	v_mov_b32_e32 v55, v103
	v_mov_b32_e32 v10, v104
	v_mov_b32_e32 v11, v105
	v_mov_b32_e32 v12, v106
	v_mov_b32_e32 v13, v107
	v_mov_b32_e32 v120, v108
	v_mov_b32_e32 v121, v109
	v_mov_b32_e32 v122, v110
	v_mov_b32_e32 v123, v111
	s_add_i32 s15, s1, 4
	s_min_u32 s15, s15, s16
	s_add_i32 s12, s7, s15
	v_mad_i64_i32 v[112:113], s[44:45], s12, v233, v[14:15]
	global_load_dwordx4 v[100:103], v[112:113], off
	v_add_u32_e32 v114, s15, v9
	v_mad_i64_i32 v[114:115], s[44:45], v114, s29, v[14:15]
	global_load_dwordx4 v[104:107], v[114:115], off
	global_load_dwordx4 v[108:111], v[112:113], off offset:1024
	s_add_i32 s12, s0, s1
	v_mov_b32_e32 v38, 0
	v_mov_b32_e32 v39, 0
	v_mov_b32_e32 v40, 0
	v_mov_b32_e32 v41, 0
	v_mov_b32_e32 v42, 0
	v_mov_b32_e32 v43, 0
	v_mov_b32_e32 v46, 0
	s_cmpk_lt_i32 s12, 0x70
	v_mov_b32_e32 v47, 0
	v_lshlrev_b32_e32 v48, 16, v52
	v_and_b32_e32 v49, 0xffff0000, v52
	v_lshlrev_b32_e32 v36, 16, v53
	v_and_b32_e32 v37, 0xffff0000, v53
	v_lshlrev_b32_e32 v44, 16, v54
	v_and_b32_e32 v45, 0xffff0000, v54
	v_lshlrev_b32_e32 v34, 16, v55
	v_and_b32_e32 v35, 0xffff0000, v55
	v_pk_add_f32 v[28:29], v[28:29], v[48:49]
	v_pk_add_f32 v[30:31], v[30:31], v[36:37]
	v_pk_add_f32 v[32:33], v[32:33], v[44:45]
	v_pk_add_f32 v[26:27], v[26:27], v[34:35]
	s_cbranch_scc1 .Lpool_t3
	v_mov_b32_e32 v38, v120
	v_mov_b32_e32 v39, v121
	v_mov_b32_e32 v40, v122
	v_mov_b32_e32 v41, v123
	s_addk_i32 s12, 0xff91
	v_min_i32_e32 v21, s12, v17
	v_cvt_f32_u32_e32 v21, v21
	v_div_scale_f32 v23, s[12:13], v21, v21, 1.0
	v_rcp_f32_e32 v42, v23
	v_div_scale_f32 v43, vcc, 1.0, v21, 1.0
	v_fma_f32 v46, -v23, v42, 1.0
	v_fmac_f32_e32 v42, v46, v42
	v_mul_f32_e32 v46, v43, v42
	v_fma_f32 v47, -v23, v46, v43
	v_fmac_f32_e32 v46, v47, v42
	v_fma_f32 v23, -v23, v46, v43
	v_div_fmas_f32 v23, v23, v42, v46
	v_div_fixup_f32 v42, v23, v21, 1.0
	v_pk_fma_f32 v[46:47], v[42:43], v[28:29], v[48:49] op_sel_hi:[0,1,1] neg_lo:[0,0,1] neg_hi:[0,0,1]
	v_fma_f32 v21, v42, v30, -v36
	v_fma_f32 v23, v42, v26, -v34
	v_fma_f32 v34, v42, v31, -v37
	v_fma_f32 v36, v42, v27, -v35
	v_pk_fma_f32 v[44:45], v[42:43], v[32:33], v[44:45] op_sel_hi:[0,1,1] neg_lo:[0,0,1] neg_hi:[0,0,1]
	v_pk_mul_f32 v[42:43], v[2:3], v[46:47]
	v_mul_f32_e32 v46, v4, v21
	v_mul_f32_e32 v48, v8, v23
	v_pk_mul_f32 v[44:45], v[6:7], v[44:45]
	v_and_b32_e32 v35, 0xffff0000, v39
	v_and_b32_e32 v37, 0xffff0000, v41
	v_lshlrev_b32_e32 v52, 16, v38
	v_and_b32_e32 v53, 0xffff0000, v38
	v_lshlrev_b32_e32 v47, 16, v39
	v_lshlrev_b32_e32 v49, 16, v41
	v_lshlrev_b32_e32 v38, 16, v40
	v_and_b32_e32 v39, 0xffff0000, v40
	v_mul_f32_e32 v21, 0xbfb8aa3b, v52
	v_mul_f32_e32 v23, 0xbfb8aa3b, v53
	v_mul_f32_e32 v55, 0xbfb8aa3b, v35
	v_mul_f32_e32 v56, 0xbfb8aa3b, v37
	v_mul_f32_e32 v40, 0xbfb8aa3b, v38
	v_mul_f32_e32 v41, 0xbfb8aa3b, v39
	v_mul_f32_e32 v51, 0xbfb8aa3b, v47
	v_mul_f32_e32 v54, 0xbfb8aa3b, v49
	v_exp_f32_e32 v21, v21
	v_exp_f32_e32 v23, v23
	v_exp_f32_e32 v55, v55
	v_exp_f32_e32 v56, v56
	v_exp_f32_e32 v40, v40
	v_exp_f32_e32 v41, v41
	v_exp_f32_e32 v51, v51
	v_exp_f32_e32 v54, v54
	v_add_f32_e32 v21, 1.0, v21
	v_add_f32_e32 v23, 1.0, v23
	v_add_f32_e32 v60, 1.0, v55
	v_add_f32_e32 v56, 1.0, v56
	v_add_f32_e32 v57, 1.0, v40
	v_add_f32_e32 v58, 1.0, v41
	v_add_f32_e32 v51, 1.0, v51
	v_add_f32_e32 v59, 1.0, v54
	v_rcp_f32_e32 v40, v21
	v_rcp_f32_e32 v41, v23
	v_rcp_f32_e32 v21, v60
	v_rcp_f32_e32 v23, v56
	v_rcp_f32_e32 v54, v57
	v_rcp_f32_e32 v55, v58
	v_rcp_f32_e32 v51, v51
	v_rcp_f32_e32 v57, v59
	v_pk_mul_f32 v[34:35], v[20:21], v[34:35]
	v_pk_mul_f32 v[36:37], v[22:23], v[36:37]
	v_pk_mul_f32 v[40:41], v[40:41], v[52:53]
	v_pk_mul_f32 v[52:53], v[54:55], v[38:39]
	v_mul_f32_e32 v54, v51, v47
	v_mul_f32_e32 v56, v57, v49
	v_mov_b32_e32 v47, v34
	v_mov_b32_e32 v55, v35
	v_mov_b32_e32 v49, v36
	v_mov_b32_e32 v57, v37
	v_pk_mul_f32 v[38:39], v[42:43], v[40:41]
	v_pk_mul_f32 v[42:43], v[44:45], v[52:53]
	v_pk_mul_f32 v[40:41], v[46:47], v[54:55]
	v_pk_mul_f32 v[46:47], v[48:49], v[56:57]
.Lpool_t3:
	s_add_i32 s1, s1, 1
	v_lshlrev_b32_e32 v34, 16, v10
	v_and_b32_e32 v35, 0xffff0000, v10
	v_lshlrev_b32_e32 v36, 16, v11
	v_and_b32_e32 v37, 0xffff0000, v11
	v_lshlrev_b32_e32 v44, 16, v12
	v_and_b32_e32 v45, 0xffff0000, v12
	v_lshlrev_b32_e32 v48, 16, v13
	v_and_b32_e32 v49, 0xffff0000, v13
	v_cmp_ne_u32_e32 vcc, s1, v5
	v_pk_add_f32 v[28:29], v[28:29], v[34:35] neg_lo:[0,1] neg_hi:[0,1]
	v_pk_add_f32 v[30:31], v[30:31], v[36:37] neg_lo:[0,1] neg_hi:[0,1]
	v_pk_add_f32 v[32:33], v[32:33], v[44:45] neg_lo:[0,1] neg_hi:[0,1]
	s_and_b64 vcc, exec, vcc
	v_pk_add_f32 v[26:27], v[26:27], v[48:49] neg_lo:[0,1] neg_hi:[0,1]
	v_cvt_pk_bf16_f32 v10, v38, v39
	v_cvt_pk_bf16_f32 v11, v40, v41
	v_cvt_pk_bf16_f32 v12, v42, v43
	v_cvt_pk_bf16_f32 v13, v46, v47
	global_store_dwordx4 v[24:25], v[10:13], off offset:1024
	s_cbranch_vccz .LBB0_227
	s_branch .Lpool_u0
